# fused final-norm epilogue with sc1 partial-sum protocol (no attention stagger) - reference point
# speedup vs baseline: 1.0313x; 1.0071x over previous
.LBB0_1169:
	ds_read_b128 v[128:131], v167
	ds_read_b128 v[132:135], v167 offset:1024
	ds_read_b128 v[136:139], v167 offset:2048
	ds_read_b128 v[156:159], v167 offset:3072
	s_add_u32 s6, s40, 0x100
	s_addc_u32 s7, s41, 0
	s_cmp_eq_u32 s65, 40
	s_cselect_b32 s45, s1, s7
	s_cselect_b32 s44, s0, s6
	s_cselect_b32 s43, s39, s64
	s_cselect_b32 s42, s38, s63
	v_lshl_add_u64 v[202:203], s[40:41], 0, v[148:149]
	s_add_i32 m0, s47, 0xc000
	ds_read_b128 v[160:163], v168
	ds_read_b128 v[172:175], v168 offset:1024
	ds_read_b128 v[176:179], v168 offset:2048
	ds_read_b128 v[180:183], v168 offset:3072
	ds_read_b128 v[184:187], v168 offset:4096
	ds_read_b128 v[188:191], v168 offset:5120
	ds_read_b128 v[194:197], v168 offset:6144
	ds_read_b128 v[198:201], v168 offset:7168
	global_load_lds_dwordx4 v[202:203], off
	v_lshl_add_u64 v[202:203], s[40:41], 0, v[150:151]
	s_add_i32 m0, s47, 0xe000
	s_nop 0
	global_load_lds_dwordx4 v[202:203], off
	s_waitcnt lgkmcnt(8)
	s_barrier
	s_waitcnt lgkmcnt(0)
	s_setprio 1
	s_waitcnt lgkmcnt(0)
	v_mfma_f32_16x16x32_bf16 v[124:127], v[128:131], v[160:163], v[124:127]
	v_mfma_f32_16x16x32_bf16 v[120:123], v[136:139], v[160:163], v[120:123]
	v_mfma_f32_16x16x32_bf16 v[108:111], v[128:131], v[176:179], v[108:111]
	v_mfma_f32_16x16x32_bf16 v[104:107], v[136:139], v[176:179], v[104:107]
	v_mfma_f32_16x16x32_bf16 v[92:95], v[128:131], v[184:187], v[92:95]
	v_mfma_f32_16x16x32_bf16 v[88:91], v[136:139], v[184:187], v[88:91]
	v_mfma_f32_16x16x32_bf16 v[76:79], v[128:131], v[194:197], v[76:79]
	v_mfma_f32_16x16x32_bf16 v[72:75], v[136:139], v[194:197], v[72:75]
	v_mfma_f32_16x16x32_bf16 v[124:127], v[132:135], v[172:175], v[124:127]
	v_mfma_f32_16x16x32_bf16 v[120:123], v[156:159], v[172:175], v[120:123]
	v_mfma_f32_16x16x32_bf16 v[108:111], v[132:135], v[180:183], v[108:111]
	v_mfma_f32_16x16x32_bf16 v[104:107], v[156:159], v[180:183], v[104:107]
	v_mfma_f32_16x16x32_bf16 v[92:95], v[132:135], v[188:191], v[92:95]
	v_mfma_f32_16x16x32_bf16 v[88:91], v[156:159], v[188:191], v[88:91]
	v_mfma_f32_16x16x32_bf16 v[76:79], v[132:135], v[198:201], v[76:79]
	v_mfma_f32_16x16x32_bf16 v[72:75], v[156:159], v[198:201], v[72:75]
	s_setprio 0
	s_barrier
	s_add_i32 s28, s57, s46
	v_lshl_add_u64 v[218:219], s[42:43], 0, v[142:143]
	s_mov_b32 m0, s28
	ds_read_b128 v[202:205], v169
	ds_read_b128 v[206:209], v169 offset:1024
	ds_read_b128 v[210:213], v169 offset:2048
	ds_read_b128 v[214:217], v169 offset:3072
	global_load_lds_dwordx4 v[218:219], off
	v_lshl_add_u64 v[220:221], s[42:43], 0, v[146:147]
	s_add_i32 m0, s28, 0x2000
	s_nop 0
	global_load_lds_dwordx4 v[220:221], off
	s_barrier
	s_waitcnt lgkmcnt(0)
	s_setprio 1
	s_waitcnt lgkmcnt(0)
	v_mfma_f32_16x16x32_bf16 v[116:119], v[202:205], v[160:163], v[116:119]
	v_mfma_f32_16x16x32_bf16 v[112:115], v[210:213], v[160:163], v[112:115]
	v_mfma_f32_16x16x32_bf16 v[100:103], v[202:205], v[176:179], v[100:103]
	v_mfma_f32_16x16x32_bf16 v[96:99], v[210:213], v[176:179], v[96:99]
	v_mfma_f32_16x16x32_bf16 v[84:87], v[202:205], v[184:187], v[84:87]
	v_mfma_f32_16x16x32_bf16 v[80:83], v[210:213], v[184:187], v[80:83]
	v_mfma_f32_16x16x32_bf16 v[68:71], v[202:205], v[194:197], v[68:71]
	v_mfma_f32_16x16x32_bf16 v[64:67], v[210:213], v[194:197], v[64:67]
	v_mfma_f32_16x16x32_bf16 v[116:119], v[206:209], v[172:175], v[116:119]
	v_mfma_f32_16x16x32_bf16 v[112:115], v[214:217], v[172:175], v[112:115]
	v_mfma_f32_16x16x32_bf16 v[100:103], v[206:209], v[180:183], v[100:103]
	v_mfma_f32_16x16x32_bf16 v[96:99], v[214:217], v[180:183], v[96:99]
	v_mfma_f32_16x16x32_bf16 v[84:87], v[206:209], v[188:191], v[84:87]
	v_mfma_f32_16x16x32_bf16 v[80:83], v[214:217], v[188:191], v[80:83]
	v_mfma_f32_16x16x32_bf16 v[68:71], v[206:209], v[198:201], v[68:71]
	v_mfma_f32_16x16x32_bf16 v[64:67], v[214:217], v[198:201], v[64:67]
	s_setprio 0
	s_mov_b32 m0, s47
	v_lshl_add_u64 v[222:223], s[44:45], 0, v[140:141]
	s_barrier
	ds_read_b128 v[160:163], v168 offset:16384
	ds_read_b128 v[172:175], v168 offset:17408
	ds_read_b128 v[176:179], v168 offset:18432
	ds_read_b128 v[180:183], v168 offset:19456
	ds_read_b128 v[184:187], v168 offset:20480
	ds_read_b128 v[188:191], v168 offset:21504
	ds_read_b128 v[194:197], v168 offset:22528
	ds_read_b128 v[198:201], v168 offset:23552
	global_load_lds_dwordx4 v[222:223], off
	v_lshl_add_u64 v[224:225], s[44:45], 0, v[144:145]
	s_mov_b32 m0, s48
	s_nop 0
	global_load_lds_dwordx4 v[224:225], off
	s_barrier
	s_waitcnt lgkmcnt(0)
	s_setprio 1
	s_waitcnt lgkmcnt(0)
	v_mfma_f32_16x16x32_bf16 v[60:63], v[128:131], v[160:163], v[60:63]
	v_mfma_f32_16x16x32_bf16 v[56:59], v[136:139], v[160:163], v[56:59]
	v_mfma_f32_16x16x32_bf16 v[44:47], v[128:131], v[176:179], v[44:47]
	v_mfma_f32_16x16x32_bf16 v[40:43], v[136:139], v[176:179], v[40:43]
	v_mfma_f32_16x16x32_bf16 v[28:31], v[128:131], v[184:187], v[28:31]
	v_mfma_f32_16x16x32_bf16 v[24:27], v[136:139], v[184:187], v[24:27]
	v_mfma_f32_16x16x32_bf16 v[12:15], v[128:131], v[194:197], v[12:15]
	v_mfma_f32_16x16x32_bf16 v[8:11], v[136:139], v[194:197], v[8:11]
	v_mfma_f32_16x16x32_bf16 v[60:63], v[132:135], v[172:175], v[60:63]
	v_mfma_f32_16x16x32_bf16 v[56:59], v[156:159], v[172:175], v[56:59]
	v_mfma_f32_16x16x32_bf16 v[44:47], v[132:135], v[180:183], v[44:47]
	v_mfma_f32_16x16x32_bf16 v[40:43], v[156:159], v[180:183], v[40:43]
	v_mfma_f32_16x16x32_bf16 v[28:31], v[132:135], v[188:191], v[28:31]
	v_mfma_f32_16x16x32_bf16 v[24:27], v[156:159], v[188:191], v[24:27]
	v_mfma_f32_16x16x32_bf16 v[12:15], v[132:135], v[198:201], v[12:15]
	v_mfma_f32_16x16x32_bf16 v[8:11], v[156:159], v[198:201], v[8:11]
	s_setprio 0
	s_barrier
	s_add_u32 s40, s42, 0x2c000
	s_addc_u32 s41, s43, 0
	s_add_i32 s28, s58, s46
	v_lshl_add_u64 v[128:129], s[40:41], 0, v[142:143]
	s_mov_b32 m0, s28
	s_nop 0
	global_load_lds_dwordx4 v[128:129], off
	v_lshl_add_u64 v[128:129], s[40:41], 0, v[146:147]
	s_add_i32 m0, s28, 0x2000
	s_nop 0
	global_load_lds_dwordx4 v[128:129], off
	s_waitcnt vmcnt(6)
	s_barrier
	s_setprio 1
	v_mfma_f32_16x16x32_bf16 v[52:55], v[202:205], v[160:163], v[52:55]
	v_mfma_f32_16x16x32_bf16 v[48:51], v[210:213], v[160:163], v[48:51]
	v_mfma_f32_16x16x32_bf16 v[36:39], v[202:205], v[176:179], v[36:39]
	v_mfma_f32_16x16x32_bf16 v[32:35], v[210:213], v[176:179], v[32:35]
	v_mfma_f32_16x16x32_bf16 v[20:23], v[202:205], v[184:187], v[20:23]
	v_mfma_f32_16x16x32_bf16 v[16:19], v[210:213], v[184:187], v[16:19]
	v_mfma_f32_16x16x32_bf16 v[4:7], v[202:205], v[194:197], v[4:7]
	v_mfma_f32_16x16x32_bf16 v[0:3], v[210:213], v[194:197], v[0:3]
	v_mfma_f32_16x16x32_bf16 v[52:55], v[206:209], v[172:175], v[52:55]
	v_mfma_f32_16x16x32_bf16 v[48:51], v[214:217], v[172:175], v[48:51]
	v_mfma_f32_16x16x32_bf16 v[36:39], v[206:209], v[180:183], v[36:39]
	v_mfma_f32_16x16x32_bf16 v[32:35], v[214:217], v[180:183], v[32:35]
	v_mfma_f32_16x16x32_bf16 v[20:23], v[206:209], v[188:191], v[20:23]
	v_mfma_f32_16x16x32_bf16 v[16:19], v[214:217], v[188:191], v[16:19]
	v_mfma_f32_16x16x32_bf16 v[4:7], v[206:209], v[198:201], v[4:7]
	v_mfma_f32_16x16x32_bf16 v[0:3], v[214:217], v[198:201], v[0:3]
	s_setprio 0
	s_add_i32 s28, 0, 0x18000
	v_add_u32_e32 v156, s28, v165
	s_barrier
	ds_read_b128 v[128:131], v156
	ds_read_b128 v[132:135], v156 offset:1024
	ds_read_b128 v[136:139], v156 offset:2048
	ds_read_b128 v[156:159], v156 offset:3072
	s_add_u32 s40, s44, 0xb0000
	s_addc_u32 s41, s45, 0
	s_mov_b32 m0, s49
	v_lshl_add_u64 v[202:203], s[40:41], 0, v[140:141]
	ds_read_b128 v[160:163], v168 offset:32768
	ds_read_b128 v[172:175], v168 offset:33792
	ds_read_b128 v[176:179], v168 offset:34816
	ds_read_b128 v[180:183], v168 offset:35840
	ds_read_b128 v[184:187], v168 offset:36864
	ds_read_b128 v[188:191], v168 offset:37888
	ds_read_b128 v[194:197], v168 offset:38912
	ds_read_b128 v[198:201], v168 offset:39936
	global_load_lds_dwordx4 v[202:203], off
	v_lshl_add_u64 v[202:203], s[40:41], 0, v[144:145]
	s_mov_b32 m0, s50
	s_nop 0
	global_load_lds_dwordx4 v[202:203], off
	s_waitcnt lgkmcnt(8)
	s_barrier
	s_waitcnt lgkmcnt(0)
	s_setprio 1
	s_waitcnt lgkmcnt(0)
	v_mfma_f32_16x16x32_bf16 v[124:127], v[128:131], v[160:163], v[124:127]
	v_mfma_f32_16x16x32_bf16 v[120:123], v[136:139], v[160:163], v[120:123]
	v_mfma_f32_16x16x32_bf16 v[108:111], v[128:131], v[176:179], v[108:111]
	v_mfma_f32_16x16x32_bf16 v[104:107], v[136:139], v[176:179], v[104:107]
	v_mfma_f32_16x16x32_bf16 v[92:95], v[128:131], v[184:187], v[92:95]
	v_mfma_f32_16x16x32_bf16 v[88:91], v[136:139], v[184:187], v[88:91]
	v_mfma_f32_16x16x32_bf16 v[76:79], v[128:131], v[194:197], v[76:79]
	v_mfma_f32_16x16x32_bf16 v[72:75], v[136:139], v[194:197], v[72:75]
	v_mfma_f32_16x16x32_bf16 v[124:127], v[132:135], v[172:175], v[124:127]
	v_mfma_f32_16x16x32_bf16 v[120:123], v[156:159], v[172:175], v[120:123]
	v_mfma_f32_16x16x32_bf16 v[108:111], v[132:135], v[180:183], v[108:111]
	v_mfma_f32_16x16x32_bf16 v[104:107], v[156:159], v[180:183], v[104:107]
	v_mfma_f32_16x16x32_bf16 v[92:95], v[132:135], v[188:191], v[92:95]
	v_mfma_f32_16x16x32_bf16 v[88:91], v[156:159], v[188:191], v[88:91]
	v_mfma_f32_16x16x32_bf16 v[76:79], v[132:135], v[198:201], v[76:79]
	v_mfma_f32_16x16x32_bf16 v[72:75], v[156:159], v[198:201], v[72:75]
	s_setprio 0
	s_barrier
	s_add_i32 s29, 0, 0x1c000
	s_add_i32 s28, s28, s46
	v_add_u32_e32 v171, s29, v165
	v_lshl_add_u64 v[218:219], v[218:219], 0, s[36:37]
	s_mov_b32 m0, s28
	ds_read_b128 v[202:205], v171
	ds_read_b128 v[206:209], v171 offset:1024
	ds_read_b128 v[210:213], v171 offset:2048
	ds_read_b128 v[214:217], v171 offset:3072
	global_load_lds_dwordx4 v[218:219], off
	v_lshl_add_u64 v[218:219], v[220:221], 0, s[36:37]
	s_add_i32 m0, s28, 0x2000
	s_nop 0
	global_load_lds_dwordx4 v[218:219], off
	s_barrier
	s_waitcnt lgkmcnt(0)
	s_setprio 1
	s_waitcnt lgkmcnt(0)
	v_mfma_f32_16x16x32_bf16 v[116:119], v[202:205], v[160:163], v[116:119]
	v_mfma_f32_16x16x32_bf16 v[112:115], v[210:213], v[160:163], v[112:115]
	v_mfma_f32_16x16x32_bf16 v[100:103], v[202:205], v[176:179], v[100:103]
	v_mfma_f32_16x16x32_bf16 v[96:99], v[210:213], v[176:179], v[96:99]
	v_mfma_f32_16x16x32_bf16 v[84:87], v[202:205], v[184:187], v[84:87]
	v_mfma_f32_16x16x32_bf16 v[80:83], v[210:213], v[184:187], v[80:83]
	v_mfma_f32_16x16x32_bf16 v[68:71], v[202:205], v[194:197], v[68:71]
	v_mfma_f32_16x16x32_bf16 v[64:67], v[210:213], v[194:197], v[64:67]
	v_mfma_f32_16x16x32_bf16 v[116:119], v[206:209], v[172:175], v[116:119]
	v_mfma_f32_16x16x32_bf16 v[112:115], v[214:217], v[172:175], v[112:115]
	v_mfma_f32_16x16x32_bf16 v[100:103], v[206:209], v[180:183], v[100:103]
	v_mfma_f32_16x16x32_bf16 v[96:99], v[214:217], v[180:183], v[96:99]
	v_mfma_f32_16x16x32_bf16 v[84:87], v[206:209], v[188:191], v[84:87]
	v_mfma_f32_16x16x32_bf16 v[80:83], v[214:217], v[188:191], v[80:83]
	v_mfma_f32_16x16x32_bf16 v[68:71], v[206:209], v[198:201], v[68:71]
	v_mfma_f32_16x16x32_bf16 v[64:67], v[214:217], v[198:201], v[64:67]
	s_setprio 0
	s_mov_b32 m0, s54
	v_lshl_add_u64 v[218:219], v[222:223], 0, s[36:37]
	s_barrier
	ds_read_b128 v[160:163], v168 offset:49152
	ds_read_b128 v[172:175], v168 offset:50176
	ds_read_b128 v[176:179], v168 offset:51200
	ds_read_b128 v[180:183], v168 offset:52224
	ds_read_b128 v[184:187], v168 offset:53248
	ds_read_b128 v[188:191], v168 offset:54272
	ds_read_b128 v[194:197], v168 offset:55296
	ds_read_b128 v[198:201], v168 offset:56320
	global_load_lds_dwordx4 v[218:219], off
	v_lshl_add_u64 v[218:219], v[224:225], 0, s[36:37]
	s_mov_b32 m0, s55
	s_nop 0
	global_load_lds_dwordx4 v[218:219], off
	s_barrier
	s_waitcnt lgkmcnt(0)
	s_setprio 1
	s_waitcnt lgkmcnt(0)
	v_mfma_f32_16x16x32_bf16 v[60:63], v[128:131], v[160:163], v[60:63]
	v_mfma_f32_16x16x32_bf16 v[56:59], v[136:139], v[160:163], v[56:59]
	v_mfma_f32_16x16x32_bf16 v[44:47], v[128:131], v[176:179], v[44:47]
	v_mfma_f32_16x16x32_bf16 v[40:43], v[136:139], v[176:179], v[40:43]
	v_mfma_f32_16x16x32_bf16 v[28:31], v[128:131], v[184:187], v[28:31]
	v_mfma_f32_16x16x32_bf16 v[24:27], v[136:139], v[184:187], v[24:27]
	v_mfma_f32_16x16x32_bf16 v[12:15], v[128:131], v[194:197], v[12:15]
	v_mfma_f32_16x16x32_bf16 v[8:11], v[136:139], v[194:197], v[8:11]
	v_mfma_f32_16x16x32_bf16 v[60:63], v[132:135], v[172:175], v[60:63]
	v_mfma_f32_16x16x32_bf16 v[56:59], v[156:159], v[172:175], v[56:59]
	v_mfma_f32_16x16x32_bf16 v[44:47], v[132:135], v[180:183], v[44:47]
	v_mfma_f32_16x16x32_bf16 v[40:43], v[156:159], v[180:183], v[40:43]
	v_mfma_f32_16x16x32_bf16 v[28:31], v[132:135], v[188:191], v[28:31]
	v_mfma_f32_16x16x32_bf16 v[24:27], v[156:159], v[188:191], v[24:27]
	v_mfma_f32_16x16x32_bf16 v[12:15], v[132:135], v[198:201], v[12:15]
	v_mfma_f32_16x16x32_bf16 v[8:11], v[156:159], v[198:201], v[8:11]
	s_setprio 0
	s_barrier
	s_add_u32 s40, s42, 0x2c080
	s_addc_u32 s41, s43, 0
	s_add_i32 s28, s29, s46
	v_lshl_add_u64 v[128:129], s[40:41], 0, v[142:143]
	s_mov_b32 m0, s28
	s_nop 0
	global_load_lds_dwordx4 v[128:129], off
	v_lshl_add_u64 v[128:129], s[40:41], 0, v[146:147]
	s_add_i32 m0, s28, 0x2000
	s_nop 0
	global_load_lds_dwordx4 v[128:129], off
	s_waitcnt vmcnt(6)
	s_barrier
	s_setprio 1
	v_mfma_f32_16x16x32_bf16 v[52:55], v[202:205], v[160:163], v[52:55]
	v_mfma_f32_16x16x32_bf16 v[48:51], v[210:213], v[160:163], v[48:51]
	v_mfma_f32_16x16x32_bf16 v[36:39], v[202:205], v[176:179], v[36:39]
	v_mfma_f32_16x16x32_bf16 v[32:35], v[210:213], v[176:179], v[32:35]
	v_mfma_f32_16x16x32_bf16 v[20:23], v[202:205], v[184:187], v[20:23]
	v_mfma_f32_16x16x32_bf16 v[16:19], v[210:213], v[184:187], v[16:19]
	v_mfma_f32_16x16x32_bf16 v[4:7], v[202:205], v[194:197], v[4:7]
	v_mfma_f32_16x16x32_bf16 v[0:3], v[210:213], v[194:197], v[0:3]
	v_mfma_f32_16x16x32_bf16 v[52:55], v[206:209], v[172:175], v[52:55]
	v_mfma_f32_16x16x32_bf16 v[48:51], v[214:217], v[172:175], v[48:51]
	v_mfma_f32_16x16x32_bf16 v[36:39], v[206:209], v[180:183], v[36:39]
	v_mfma_f32_16x16x32_bf16 v[32:35], v[214:217], v[180:183], v[32:35]
	v_mfma_f32_16x16x32_bf16 v[20:23], v[206:209], v[188:191], v[20:23]
	v_mfma_f32_16x16x32_bf16 v[16:19], v[214:217], v[188:191], v[16:19]
	v_mfma_f32_16x16x32_bf16 v[4:7], v[206:209], v[198:201], v[4:7]
	v_mfma_f32_16x16x32_bf16 v[0:3], v[214:217], v[198:201], v[0:3]
	s_setprio 0
	s_add_i32 s65, s65, 2
	s_add_u32 s63, s63, 0x100
	s_addc_u32 s64, s64, 0
	s_cmp_gt_u32 s65, 41
	s_mov_b64 s[40:41], s[6:7]
	s_barrier
	s_cbranch_scc0 .LBB0_1169
	v_lshl_add_u32 v171, s62, 8, v164
	v_lshl_or_b32 v188, s10, 8, v166
	s_mov_b32 s63, 0xffff0000
	v_lshlrev_b32_e32 v128, 11, v171
	v_lshl_add_u32 v128, v188, 1, v128
	v_lshlrev_b32_e32 v129, 12, v171
	v_lshl_add_u32 v129, v188, 2, v129
	v_lshlrev_b32_e32 v132, 2, v188
	s_mov_b64 s[70:71], s[68:69]
	global_load_dwordx4 v[194:197], v128, s[70:71]
	global_load_dwordx4 v[198:201], v128, s[70:71] offset:64
	s_add_u32 s70, s70, 0x8000
	s_addc_u32 s71, s71, 0
	global_load_dwordx4 v[202:205], v128, s[70:71]
	global_load_dwordx4 v[206:209], v128, s[70:71] offset:64
	s_add_u32 s70, s70, 0x8000
	s_addc_u32 s71, s71, 0
	global_load_dwordx4 v[210:213], v128, s[70:71]
	global_load_dwordx4 v[214:217], v128, s[70:71] offset:64
	s_add_u32 s70, s70, 0x8000
	s_addc_u32 s71, s71, 0
	global_load_dwordx4 v[218:221], v128, s[70:71]
	global_load_dwordx4 v[222:225], v128, s[70:71] offset:64
	s_add_u32 s70, s70, 0x28000
	s_addc_u32 s71, s71, 0
	global_load_dwordx4 v[226:229], v128, s[70:71]
	global_load_dwordx4 v[230:233], v128, s[70:71] offset:64
	s_add_u32 s70, s70, 0x8000
	s_addc_u32 s71, s71, 0
	global_load_dwordx4 v[234:237], v128, s[70:71]
	global_load_dwordx4 v[238:241], v128, s[70:71] offset:64
	s_add_u32 s70, s70, 0x8000
	s_addc_u32 s71, s71, 0
	global_load_dwordx4 v[172:175], v128, s[70:71]
	global_load_dwordx4 v[176:179], v128, s[70:71] offset:64
	s_add_u32 s70, s70, 0x8000
	s_addc_u32 s71, s71, 0
	global_load_dwordx4 v[180:183], v128, s[70:71]
	global_load_dwordx4 v[184:187], v128, s[70:71] offset:64
	s_bfe_u32 s42, s17, 0x20006
	s_lshl_b32 s43, s10, 4
	s_lshl_b32 s42, s42, 2
	s_add_i32 s43, s43, s42
	v_lshl_add_u32 v130, v171, 6, s43
	v_and_b32_e32 v131, 48, v170
	v_lshl_add_u32 v131, v171, 6, v131
	v_xor_b32_e32 v134, 16, v170
	v_xor_b32_e32 v135, 32, v170
	v_lshlrev_b32_e32 v134, 2, v134
	v_lshlrev_b32_e32 v135, 2, v135
	v_cmp_gt_u32_e64 s[64:65], 16, v170
	s_add_u32 s74, s8, 0x2000
	s_addc_u32 s75, s9, 0
	s_lshl_b32 s42, s62, 7
	s_add_u32 s78, s26, 0x3c08000
	s_addc_u32 s79, s27, 0
	s_add_u32 s78, s78, s42
	s_addc_u32 s79, s79, 0
	s_waitcnt vmcnt(14)
	v_lshlrev_b32_e32 v136, 16, v194
	v_and_b32_e32 v137, s63, v194
	v_pk_add_f32 v[124:125], v[124:125], v[136:137]
	v_lshlrev_b32_e32 v138, 16, v195
	v_and_b32_e32 v139, s63, v195
	v_pk_add_f32 v[126:127], v[126:127], v[138:139]
	v_lshlrev_b32_e32 v190, 16, v196
	v_and_b32_e32 v191, s63, v196
	v_pk_add_f32 v[120:121], v[120:121], v[190:191]
	v_lshlrev_b32_e32 v136, 16, v197
	v_and_b32_e32 v137, s63, v197
	v_pk_add_f32 v[122:123], v[122:123], v[136:137]
	v_lshlrev_b32_e32 v138, 16, v198
	v_and_b32_e32 v139, s63, v198
	v_pk_add_f32 v[116:117], v[116:117], v[138:139]
	v_lshlrev_b32_e32 v190, 16, v199
	v_and_b32_e32 v191, s63, v199
	v_pk_add_f32 v[118:119], v[118:119], v[190:191]
	v_lshlrev_b32_e32 v136, 16, v200
	v_and_b32_e32 v137, s63, v200
	v_pk_add_f32 v[112:113], v[112:113], v[136:137]
	v_lshlrev_b32_e32 v138, 16, v201
	v_and_b32_e32 v139, s63, v201
	v_pk_add_f32 v[114:115], v[114:115], v[138:139]
	v_mul_f32_e32 v156, v120, v120
	v_mul_f32_e32 v189, v112, v112
	v_fmac_f32_e32 v156, v121, v121
	v_fmac_f32_e32 v189, v113, v113
	v_fmac_f32_e32 v156, v122, v122
	v_fmac_f32_e32 v189, v114, v114
	v_fmac_f32_e32 v156, v123, v123
	v_fmac_f32_e32 v189, v115, v115
	v_fmac_f32_e32 v156, v124, v124
	v_fmac_f32_e32 v189, v116, v116
	v_fmac_f32_e32 v156, v125, v125
	v_fmac_f32_e32 v189, v117, v117
	v_fmac_f32_e32 v156, v126, v126
	v_fmac_f32_e32 v189, v118, v118
	v_fmac_f32_e32 v156, v127, v127
	v_fmac_f32_e32 v189, v119, v119
	v_add_f32_e32 v156, v156, v189
	s_waitcnt vmcnt(12)
	v_lshlrev_b32_e32 v190, 16, v202
	v_and_b32_e32 v191, s63, v202
	v_pk_add_f32 v[108:109], v[108:109], v[190:191]
	v_lshlrev_b32_e32 v136, 16, v203
	v_and_b32_e32 v137, s63, v203
	v_pk_add_f32 v[110:111], v[110:111], v[136:137]
	v_lshlrev_b32_e32 v138, 16, v204
	v_and_b32_e32 v139, s63, v204
	v_pk_add_f32 v[104:105], v[104:105], v[138:139]
	v_lshlrev_b32_e32 v190, 16, v205
	v_and_b32_e32 v191, s63, v205
	v_pk_add_f32 v[106:107], v[106:107], v[190:191]
	v_lshlrev_b32_e32 v136, 16, v206
	v_and_b32_e32 v137, s63, v206
	v_pk_add_f32 v[100:101], v[100:101], v[136:137]
	v_lshlrev_b32_e32 v138, 16, v207
	v_and_b32_e32 v139, s63, v207
	v_pk_add_f32 v[102:103], v[102:103], v[138:139]
	v_lshlrev_b32_e32 v190, 16, v208
	v_and_b32_e32 v191, s63, v208
	v_pk_add_f32 v[96:97], v[96:97], v[190:191]
	v_lshlrev_b32_e32 v136, 16, v209
	v_and_b32_e32 v137, s63, v209
	v_pk_add_f32 v[98:99], v[98:99], v[136:137]
	v_mul_f32_e32 v157, v104, v104
	v_mul_f32_e32 v189, v96, v96
	v_fmac_f32_e32 v157, v105, v105
	v_fmac_f32_e32 v189, v97, v97
	v_fmac_f32_e32 v157, v106, v106
	v_fmac_f32_e32 v189, v98, v98
	v_fmac_f32_e32 v157, v107, v107
	v_fmac_f32_e32 v189, v99, v99
	v_fmac_f32_e32 v157, v108, v108
	v_fmac_f32_e32 v189, v100, v100
	v_fmac_f32_e32 v157, v109, v109
	v_fmac_f32_e32 v189, v101, v101
	v_fmac_f32_e32 v157, v110, v110
	v_fmac_f32_e32 v189, v102, v102
	v_fmac_f32_e32 v157, v111, v111
	v_fmac_f32_e32 v189, v103, v103
	v_add_f32_e32 v157, v157, v189
	s_waitcnt vmcnt(10)
	v_lshlrev_b32_e32 v138, 16, v210
	v_and_b32_e32 v139, s63, v210
	v_pk_add_f32 v[92:93], v[92:93], v[138:139]
	v_lshlrev_b32_e32 v190, 16, v211
	v_and_b32_e32 v191, s63, v211
	v_pk_add_f32 v[94:95], v[94:95], v[190:191]
	v_lshlrev_b32_e32 v136, 16, v212
	v_and_b32_e32 v137, s63, v212
	v_pk_add_f32 v[88:89], v[88:89], v[136:137]
	v_lshlrev_b32_e32 v138, 16, v213
	v_and_b32_e32 v139, s63, v213
	v_pk_add_f32 v[90:91], v[90:91], v[138:139]
	v_lshlrev_b32_e32 v190, 16, v214
	v_and_b32_e32 v191, s63, v214
	v_pk_add_f32 v[84:85], v[84:85], v[190:191]
	v_lshlrev_b32_e32 v136, 16, v215
	v_and_b32_e32 v137, s63, v215
	v_pk_add_f32 v[86:87], v[86:87], v[136:137]
	v_lshlrev_b32_e32 v138, 16, v216
	v_and_b32_e32 v139, s63, v216
	v_pk_add_f32 v[80:81], v[80:81], v[138:139]
	v_lshlrev_b32_e32 v190, 16, v217
	v_and_b32_e32 v191, s63, v217
	v_pk_add_f32 v[82:83], v[82:83], v[190:191]
	v_mul_f32_e32 v158, v88, v88
	v_mul_f32_e32 v189, v80, v80
	v_fmac_f32_e32 v158, v89, v89
	v_fmac_f32_e32 v189, v81, v81
	v_fmac_f32_e32 v158, v90, v90
	v_fmac_f32_e32 v189, v82, v82
	v_fmac_f32_e32 v158, v91, v91
	v_fmac_f32_e32 v189, v83, v83
	v_fmac_f32_e32 v158, v92, v92
	v_fmac_f32_e32 v189, v84, v84
	v_fmac_f32_e32 v158, v93, v93
	v_fmac_f32_e32 v189, v85, v85
	v_fmac_f32_e32 v158, v94, v94
	v_fmac_f32_e32 v189, v86, v86
	v_fmac_f32_e32 v158, v95, v95
	v_fmac_f32_e32 v189, v87, v87
	v_add_f32_e32 v158, v158, v189
	s_waitcnt vmcnt(8)
	v_lshlrev_b32_e32 v136, 16, v218
	v_and_b32_e32 v137, s63, v218
	v_pk_add_f32 v[76:77], v[76:77], v[136:137]
	v_lshlrev_b32_e32 v138, 16, v219
	v_and_b32_e32 v139, s63, v219
	v_pk_add_f32 v[78:79], v[78:79], v[138:139]
	v_lshlrev_b32_e32 v190, 16, v220
	v_and_b32_e32 v191, s63, v220
	v_pk_add_f32 v[72:73], v[72:73], v[190:191]
	v_lshlrev_b32_e32 v136, 16, v221
	v_and_b32_e32 v137, s63, v221
	v_pk_add_f32 v[74:75], v[74:75], v[136:137]
	v_lshlrev_b32_e32 v138, 16, v222
	v_and_b32_e32 v139, s63, v222
	v_pk_add_f32 v[68:69], v[68:69], v[138:139]
	v_lshlrev_b32_e32 v190, 16, v223
	v_and_b32_e32 v191, s63, v223
	v_pk_add_f32 v[70:71], v[70:71], v[190:191]
	v_lshlrev_b32_e32 v136, 16, v224
	v_and_b32_e32 v137, s63, v224
	v_pk_add_f32 v[64:65], v[64:65], v[136:137]
	v_lshlrev_b32_e32 v138, 16, v225
	v_and_b32_e32 v139, s63, v225
	v_pk_add_f32 v[66:67], v[66:67], v[138:139]
	v_mul_f32_e32 v159, v72, v72
	v_mul_f32_e32 v189, v64, v64
	v_fmac_f32_e32 v159, v73, v73
	v_fmac_f32_e32 v189, v65, v65
	v_fmac_f32_e32 v159, v74, v74
	v_fmac_f32_e32 v189, v66, v66
	v_fmac_f32_e32 v159, v75, v75
	v_fmac_f32_e32 v189, v67, v67
	v_fmac_f32_e32 v159, v76, v76
	v_fmac_f32_e32 v189, v68, v68
	v_fmac_f32_e32 v159, v77, v77
	v_fmac_f32_e32 v189, v69, v69
	v_fmac_f32_e32 v159, v78, v78
	v_fmac_f32_e32 v189, v70, v70
	v_fmac_f32_e32 v159, v79, v79
	v_fmac_f32_e32 v189, v71, v71
	v_add_f32_e32 v159, v159, v189
	s_waitcnt vmcnt(6)
	v_lshlrev_b32_e32 v190, 16, v226
	v_and_b32_e32 v191, s63, v226
	v_pk_add_f32 v[60:61], v[60:61], v[190:191]
	v_lshlrev_b32_e32 v136, 16, v227
	v_and_b32_e32 v137, s63, v227
	v_pk_add_f32 v[62:63], v[62:63], v[136:137]
	v_lshlrev_b32_e32 v138, 16, v228
	v_and_b32_e32 v139, s63, v228
	v_pk_add_f32 v[56:57], v[56:57], v[138:139]
	v_lshlrev_b32_e32 v190, 16, v229
	v_and_b32_e32 v191, s63, v229
	v_pk_add_f32 v[58:59], v[58:59], v[190:191]
	v_lshlrev_b32_e32 v136, 16, v230
	v_and_b32_e32 v137, s63, v230
	v_pk_add_f32 v[52:53], v[52:53], v[136:137]
	v_lshlrev_b32_e32 v138, 16, v231
	v_and_b32_e32 v139, s63, v231
	v_pk_add_f32 v[54:55], v[54:55], v[138:139]
	v_lshlrev_b32_e32 v190, 16, v232
	v_and_b32_e32 v191, s63, v232
	v_pk_add_f32 v[48:49], v[48:49], v[190:191]
	v_lshlrev_b32_e32 v136, 16, v233
	v_and_b32_e32 v137, s63, v233
	v_pk_add_f32 v[50:51], v[50:51], v[136:137]
	v_mul_f32_e32 v160, v56, v56
	v_mul_f32_e32 v189, v48, v48
	v_fmac_f32_e32 v160, v57, v57
	v_fmac_f32_e32 v189, v49, v49
	v_fmac_f32_e32 v160, v58, v58
	v_fmac_f32_e32 v189, v50, v50
	v_fmac_f32_e32 v160, v59, v59
	v_fmac_f32_e32 v189, v51, v51
	v_fmac_f32_e32 v160, v60, v60
	v_fmac_f32_e32 v189, v52, v52
	v_fmac_f32_e32 v160, v61, v61
	v_fmac_f32_e32 v189, v53, v53
	v_fmac_f32_e32 v160, v62, v62
	v_fmac_f32_e32 v189, v54, v54
	v_fmac_f32_e32 v160, v63, v63
	v_fmac_f32_e32 v189, v55, v55
	v_add_f32_e32 v160, v160, v189
	s_waitcnt vmcnt(4)
	v_lshlrev_b32_e32 v138, 16, v234
	v_and_b32_e32 v139, s63, v234
	v_pk_add_f32 v[44:45], v[44:45], v[138:139]
	v_lshlrev_b32_e32 v190, 16, v235
	v_and_b32_e32 v191, s63, v235
	v_pk_add_f32 v[46:47], v[46:47], v[190:191]
	v_lshlrev_b32_e32 v136, 16, v236
	v_and_b32_e32 v137, s63, v236
	v_pk_add_f32 v[40:41], v[40:41], v[136:137]
	v_lshlrev_b32_e32 v138, 16, v237
	v_and_b32_e32 v139, s63, v237
	v_pk_add_f32 v[42:43], v[42:43], v[138:139]
	v_lshlrev_b32_e32 v190, 16, v238
	v_and_b32_e32 v191, s63, v238
	v_pk_add_f32 v[36:37], v[36:37], v[190:191]
	v_lshlrev_b32_e32 v136, 16, v239
	v_and_b32_e32 v137, s63, v239
	v_pk_add_f32 v[38:39], v[38:39], v[136:137]
	v_lshlrev_b32_e32 v138, 16, v240
	v_and_b32_e32 v139, s63, v240
	v_pk_add_f32 v[32:33], v[32:33], v[138:139]
	v_lshlrev_b32_e32 v190, 16, v241
	v_and_b32_e32 v191, s63, v241
	v_pk_add_f32 v[34:35], v[34:35], v[190:191]
	v_mul_f32_e32 v161, v40, v40
	v_mul_f32_e32 v189, v32, v32
	v_fmac_f32_e32 v161, v41, v41
	v_fmac_f32_e32 v189, v33, v33
	v_fmac_f32_e32 v161, v42, v42
	v_fmac_f32_e32 v189, v34, v34
	v_fmac_f32_e32 v161, v43, v43
	v_fmac_f32_e32 v189, v35, v35
	v_fmac_f32_e32 v161, v44, v44
	v_fmac_f32_e32 v189, v36, v36
	v_fmac_f32_e32 v161, v45, v45
	v_fmac_f32_e32 v189, v37, v37
	v_fmac_f32_e32 v161, v46, v46
	v_fmac_f32_e32 v189, v38, v38
	v_fmac_f32_e32 v161, v47, v47
	v_fmac_f32_e32 v189, v39, v39
	v_add_f32_e32 v161, v161, v189
	s_waitcnt vmcnt(2)
	v_lshlrev_b32_e32 v136, 16, v172
	v_and_b32_e32 v137, s63, v172
	v_pk_add_f32 v[28:29], v[28:29], v[136:137]
	v_lshlrev_b32_e32 v138, 16, v173
	v_and_b32_e32 v139, s63, v173
	v_pk_add_f32 v[30:31], v[30:31], v[138:139]
	v_lshlrev_b32_e32 v190, 16, v174
	v_and_b32_e32 v191, s63, v174
	v_pk_add_f32 v[24:25], v[24:25], v[190:191]
	v_lshlrev_b32_e32 v136, 16, v175
	v_and_b32_e32 v137, s63, v175
	v_pk_add_f32 v[26:27], v[26:27], v[136:137]
	v_lshlrev_b32_e32 v138, 16, v176
	v_and_b32_e32 v139, s63, v176
	v_pk_add_f32 v[20:21], v[20:21], v[138:139]
	v_lshlrev_b32_e32 v190, 16, v177
	v_and_b32_e32 v191, s63, v177
	v_pk_add_f32 v[22:23], v[22:23], v[190:191]
	v_lshlrev_b32_e32 v136, 16, v178
	v_and_b32_e32 v137, s63, v178
	v_pk_add_f32 v[16:17], v[16:17], v[136:137]
	v_lshlrev_b32_e32 v138, 16, v179
	v_and_b32_e32 v139, s63, v179
	v_pk_add_f32 v[18:19], v[18:19], v[138:139]
	v_mul_f32_e32 v162, v24, v24
	v_mul_f32_e32 v189, v16, v16
	v_fmac_f32_e32 v162, v25, v25
	v_fmac_f32_e32 v189, v17, v17
	v_fmac_f32_e32 v162, v26, v26
	v_fmac_f32_e32 v189, v18, v18
	v_fmac_f32_e32 v162, v27, v27
	v_fmac_f32_e32 v189, v19, v19
	v_fmac_f32_e32 v162, v28, v28
	v_fmac_f32_e32 v189, v20, v20
	v_fmac_f32_e32 v162, v29, v29
	v_fmac_f32_e32 v189, v21, v21
	v_fmac_f32_e32 v162, v30, v30
	v_fmac_f32_e32 v189, v22, v22
	v_fmac_f32_e32 v162, v31, v31
	v_fmac_f32_e32 v189, v23, v23
	v_add_f32_e32 v162, v162, v189
	s_waitcnt vmcnt(0)
	v_lshlrev_b32_e32 v190, 16, v180
	v_and_b32_e32 v191, s63, v180
	v_pk_add_f32 v[12:13], v[12:13], v[190:191]
	v_lshlrev_b32_e32 v136, 16, v181
	v_and_b32_e32 v137, s63, v181
	v_pk_add_f32 v[14:15], v[14:15], v[136:137]
	v_lshlrev_b32_e32 v138, 16, v182
	v_and_b32_e32 v139, s63, v182
	v_pk_add_f32 v[8:9], v[8:9], v[138:139]
	v_lshlrev_b32_e32 v190, 16, v183
	v_and_b32_e32 v191, s63, v183
	v_pk_add_f32 v[10:11], v[10:11], v[190:191]
	v_lshlrev_b32_e32 v136, 16, v184
	v_and_b32_e32 v137, s63, v184
	v_pk_add_f32 v[4:5], v[4:5], v[136:137]
	v_lshlrev_b32_e32 v138, 16, v185
	v_and_b32_e32 v139, s63, v185
	v_pk_add_f32 v[6:7], v[6:7], v[138:139]
	v_lshlrev_b32_e32 v190, 16, v186
	v_and_b32_e32 v191, s63, v186
	v_pk_add_f32 v[0:1], v[0:1], v[190:191]
	v_lshlrev_b32_e32 v136, 16, v187
	v_and_b32_e32 v137, s63, v187
	v_pk_add_f32 v[2:3], v[2:3], v[136:137]
	v_mul_f32_e32 v163, v8, v8
	v_mul_f32_e32 v189, v0, v0
	v_fmac_f32_e32 v163, v9, v9
	v_fmac_f32_e32 v189, v1, v1
	v_fmac_f32_e32 v163, v10, v10
	v_fmac_f32_e32 v189, v2, v2
	v_fmac_f32_e32 v163, v11, v11
	v_fmac_f32_e32 v189, v3, v3
	v_fmac_f32_e32 v163, v12, v12
	v_fmac_f32_e32 v189, v4, v4
	v_fmac_f32_e32 v163, v13, v13
	v_fmac_f32_e32 v189, v5, v5
	v_fmac_f32_e32 v163, v14, v14
	v_fmac_f32_e32 v189, v6, v6
	v_fmac_f32_e32 v163, v15, v15
	v_fmac_f32_e32 v189, v7, v7
	v_add_f32_e32 v163, v163, v189
	ds_bpermute_b32 v136, v134, v156
	ds_bpermute_b32 v137, v134, v157
	ds_bpermute_b32 v138, v134, v158
	ds_bpermute_b32 v139, v134, v159
	ds_bpermute_b32 v188, v134, v160
	ds_bpermute_b32 v189, v134, v161
	ds_bpermute_b32 v190, v134, v162
	ds_bpermute_b32 v191, v134, v163
	s_waitcnt lgkmcnt(0)
	v_add_f32_e32 v156, v156, v136
	v_add_f32_e32 v157, v157, v137
	v_add_f32_e32 v158, v158, v138
	v_add_f32_e32 v159, v159, v139
	v_add_f32_e32 v160, v160, v188
	v_add_f32_e32 v161, v161, v189
	v_add_f32_e32 v162, v162, v190
	v_add_f32_e32 v163, v163, v191
	ds_bpermute_b32 v136, v135, v156
	ds_bpermute_b32 v137, v135, v157
	ds_bpermute_b32 v138, v135, v158
	ds_bpermute_b32 v139, v135, v159
	ds_bpermute_b32 v188, v135, v160
	ds_bpermute_b32 v189, v135, v161
	ds_bpermute_b32 v190, v135, v162
	ds_bpermute_b32 v191, v135, v163
	s_waitcnt lgkmcnt(0)
	v_add_f32_e32 v156, v156, v136
	v_add_f32_e32 v157, v157, v137
	v_add_f32_e32 v158, v158, v138
	v_add_f32_e32 v159, v159, v139
	v_add_f32_e32 v160, v160, v188
	v_add_f32_e32 v161, v161, v189
	v_add_f32_e32 v162, v162, v190
	v_add_f32_e32 v163, v163, v191
	s_and_saveexec_b64 s[66:67], s[64:65]
	global_store_dword v130, v156, s[8:9] sc1
	global_store_dword v130, v157, s[8:9] offset:1024 sc1
	global_store_dword v130, v158, s[8:9] offset:2048 sc1
	global_store_dword v130, v159, s[8:9] offset:3072 sc1
	global_store_dword v130, v160, s[74:75] sc1
	global_store_dword v130, v161, s[74:75] offset:1024 sc1
	global_store_dword v130, v162, s[74:75] offset:2048 sc1
	global_store_dword v130, v163, s[74:75] offset:3072 sc1
	s_or_b64 exec, exec, s[66:67]
	global_load_dwordx4 v[210:213], v132, s[22:23]
	global_load_dwordx4 v[214:217], v132, s[22:23] offset:16
	global_load_dwordx4 v[218:221], v132, s[22:23] offset:128
	global_load_dwordx4 v[222:225], v132, s[22:23] offset:144
	s_waitcnt vmcnt(0)
	s_barrier
	s_barrier
	s_cmpk_gt_u32 s17, 0xff
	s_cbranch_scc1 .Lf11_w1_a
	s_and_saveexec_b64 s[40:41], s[14:15]
	s_cbranch_execz .Lf11_t0_done
	v_mov_b32_e32 v133, 0
	v_mov_b32_e32 v189, 1
	global_atomic_add v133, v189, s[78:79]
	s_mov_b32 s80, 0

.Lf11_spin_done:
.Lf11_t0_done:
	s_or_b64 exec, exec, s[40:41]
	s_barrier
.Lf11_w1_a:
	global_load_dwordx4 v[226:229], v131, s[8:9] sc1
	global_load_dwordx4 v[230:233], v131, s[8:9] offset:1024 sc1
	global_load_dwordx4 v[234:237], v131, s[8:9] offset:2048 sc1
	global_load_dwordx4 v[238:241], v131, s[8:9] offset:3072 sc1
	global_load_dwordx4 v[172:175], v131, s[74:75] sc1
	global_load_dwordx4 v[176:179], v131, s[74:75] offset:1024 sc1
	global_load_dwordx4 v[180:183], v131, s[74:75] offset:2048 sc1
	global_load_dwordx4 v[184:187], v131, s[74:75] offset:3072 sc1
	s_mov_b64 s[76:77], s[24:25]
	s_mov_b32 s84, 0x3a800000
	v_mov_b32_e32 v133, 0x358637bd
	s_waitcnt vmcnt(7)
	v_add_f32_e32 v226, v226, v227
	v_add_f32_e32 v228, v228, v229
	v_add_f32_e32 v156, v226, v228
	s_waitcnt vmcnt(6)
	v_add_f32_e32 v230, v230, v231
	v_add_f32_e32 v232, v232, v233
	v_add_f32_e32 v157, v230, v232
	s_waitcnt vmcnt(5)
	v_add_f32_e32 v234, v234, v235
	v_add_f32_e32 v236, v236, v237
	v_add_f32_e32 v158, v234, v236
	s_waitcnt vmcnt(4)
	v_add_f32_e32 v238, v238, v239
	v_add_f32_e32 v240, v240, v241
	v_add_f32_e32 v159, v238, v240
	s_waitcnt vmcnt(3)
	v_add_f32_e32 v172, v172, v173
	v_add_f32_e32 v174, v174, v175
	v_add_f32_e32 v160, v172, v174
	s_waitcnt vmcnt(2)
	v_add_f32_e32 v176, v176, v177
	v_add_f32_e32 v178, v178, v179
	v_add_f32_e32 v161, v176, v178
	s_waitcnt vmcnt(1)
	v_add_f32_e32 v180, v180, v181
	v_add_f32_e32 v182, v182, v183
	v_add_f32_e32 v162, v180, v182
	s_waitcnt vmcnt(0)
	v_add_f32_e32 v184, v184, v185
	v_add_f32_e32 v186, v186, v187
	v_add_f32_e32 v163, v184, v186
	ds_bpermute_b32 v136, v134, v156
	ds_bpermute_b32 v137, v134, v157
	ds_bpermute_b32 v138, v134, v158
	ds_bpermute_b32 v139, v134, v159
	ds_bpermute_b32 v188, v134, v160
	ds_bpermute_b32 v189, v134, v161
	ds_bpermute_b32 v190, v134, v162
	ds_bpermute_b32 v191, v134, v163
	s_waitcnt lgkmcnt(0)
	v_add_f32_e32 v156, v156, v136
	v_add_f32_e32 v157, v157, v137
	v_add_f32_e32 v158, v158, v138
	v_add_f32_e32 v159, v159, v139
	v_add_f32_e32 v160, v160, v188
	v_add_f32_e32 v161, v161, v189
	v_add_f32_e32 v162, v162, v190
	v_add_f32_e32 v163, v163, v191
	ds_bpermute_b32 v136, v135, v156
	ds_bpermute_b32 v137, v135, v157
	ds_bpermute_b32 v138, v135, v158
	ds_bpermute_b32 v139, v135, v159
	ds_bpermute_b32 v188, v135, v160
	ds_bpermute_b32 v189, v135, v161
	ds_bpermute_b32 v190, v135, v162
	ds_bpermute_b32 v191, v135, v163
	s_waitcnt lgkmcnt(0)
	v_add_f32_e32 v156, v156, v136
	v_add_f32_e32 v157, v157, v137
	v_add_f32_e32 v158, v158, v138
	v_add_f32_e32 v159, v159, v139
	v_add_f32_e32 v160, v160, v188
	v_add_f32_e32 v161, v161, v189
	v_add_f32_e32 v162, v162, v190
	v_add_f32_e32 v163, v163, v191
	v_fma_f32 v156, v156, s84, v133
	v_fma_f32 v157, v157, s84, v133
	v_fma_f32 v158, v158, s84, v133
	v_fma_f32 v159, v159, s84, v133
	v_fma_f32 v160, v160, s84, v133
	v_fma_f32 v161, v161, s84, v133
	v_fma_f32 v162, v162, s84, v133
	v_fma_f32 v163, v163, s84, v133
	v_rsq_f32_e32 v194, v156
	v_rsq_f32_e32 v196, v157
	v_rsq_f32_e32 v198, v158
	v_rsq_f32_e32 v200, v159
	v_rsq_f32_e32 v202, v160
	v_rsq_f32_e32 v204, v161
	v_rsq_f32_e32 v206, v162
	v_rsq_f32_e32 v208, v163
	s_nop 0
	v_pk_mul_f32 v[124:125], v[124:125], v[194:195] op_sel_hi:[1,0]
	v_pk_mul_f32 v[126:127], v[126:127], v[194:195] op_sel_hi:[1,0]
	v_pk_mul_f32 v[120:121], v[120:121], v[194:195] op_sel_hi:[1,0]
	v_pk_mul_f32 v[122:123], v[122:123], v[194:195] op_sel_hi:[1,0]
	v_pk_mul_f32 v[116:117], v[116:117], v[194:195] op_sel_hi:[1,0]
	v_pk_mul_f32 v[118:119], v[118:119], v[194:195] op_sel_hi:[1,0]
	v_pk_mul_f32 v[112:113], v[112:113], v[194:195] op_sel_hi:[1,0]
	v_pk_mul_f32 v[114:115], v[114:115], v[194:195] op_sel_hi:[1,0]
	v_pk_mul_f32 v[124:125], v[124:125], v[210:211]
	v_pk_mul_f32 v[126:127], v[126:127], v[212:213]
	v_pk_mul_f32 v[120:121], v[120:121], v[214:215]
	v_pk_mul_f32 v[122:123], v[122:123], v[216:217]
	v_pk_mul_f32 v[116:117], v[116:117], v[218:219]
	v_pk_mul_f32 v[118:119], v[118:119], v[220:221]
	v_pk_mul_f32 v[112:113], v[112:113], v[222:223]
	v_pk_mul_f32 v[114:115], v[114:115], v[224:225]
	global_store_dwordx4 v129, v[124:127], s[76:77]
	global_store_dwordx4 v129, v[120:123], s[76:77] offset:16
	global_store_dwordx4 v129, v[116:119], s[76:77] offset:128
	global_store_dwordx4 v129, v[112:115], s[76:77] offset:144
	s_add_u32 s76, s76, 0x10000
	s_addc_u32 s77, s77, 0
	v_pk_mul_f32 v[108:109], v[108:109], v[196:197] op_sel_hi:[1,0]
	v_pk_mul_f32 v[110:111], v[110:111], v[196:197] op_sel_hi:[1,0]
	v_pk_mul_f32 v[104:105], v[104:105], v[196:197] op_sel_hi:[1,0]
	v_pk_mul_f32 v[106:107], v[106:107], v[196:197] op_sel_hi:[1,0]
	v_pk_mul_f32 v[100:101], v[100:101], v[196:197] op_sel_hi:[1,0]
	v_pk_mul_f32 v[102:103], v[102:103], v[196:197] op_sel_hi:[1,0]
	v_pk_mul_f32 v[96:97], v[96:97], v[196:197] op_sel_hi:[1,0]
	v_pk_mul_f32 v[98:99], v[98:99], v[196:197] op_sel_hi:[1,0]
	v_pk_mul_f32 v[108:109], v[108:109], v[210:211]
	v_pk_mul_f32 v[110:111], v[110:111], v[212:213]
	v_pk_mul_f32 v[104:105], v[104:105], v[214:215]
	v_pk_mul_f32 v[106:107], v[106:107], v[216:217]
	v_pk_mul_f32 v[100:101], v[100:101], v[218:219]
	v_pk_mul_f32 v[102:103], v[102:103], v[220:221]
	v_pk_mul_f32 v[96:97], v[96:97], v[222:223]
	v_pk_mul_f32 v[98:99], v[98:99], v[224:225]
	global_store_dwordx4 v129, v[108:111], s[76:77]
	global_store_dwordx4 v129, v[104:107], s[76:77] offset:16
	global_store_dwordx4 v129, v[100:103], s[76:77] offset:128
	global_store_dwordx4 v129, v[96:99], s[76:77] offset:144
	s_add_u32 s76, s76, 0x10000
	s_addc_u32 s77, s77, 0
	v_pk_mul_f32 v[92:93], v[92:93], v[198:199] op_sel_hi:[1,0]
	v_pk_mul_f32 v[94:95], v[94:95], v[198:199] op_sel_hi:[1,0]
	v_pk_mul_f32 v[88:89], v[88:89], v[198:199] op_sel_hi:[1,0]
	v_pk_mul_f32 v[90:91], v[90:91], v[198:199] op_sel_hi:[1,0]
	v_pk_mul_f32 v[84:85], v[84:85], v[198:199] op_sel_hi:[1,0]
	v_pk_mul_f32 v[86:87], v[86:87], v[198:199] op_sel_hi:[1,0]
	v_pk_mul_f32 v[80:81], v[80:81], v[198:199] op_sel_hi:[1,0]
	v_pk_mul_f32 v[82:83], v[82:83], v[198:199] op_sel_hi:[1,0]
	v_pk_mul_f32 v[92:93], v[92:93], v[210:211]
	v_pk_mul_f32 v[94:95], v[94:95], v[212:213]
	v_pk_mul_f32 v[88:89], v[88:89], v[214:215]
	v_pk_mul_f32 v[90:91], v[90:91], v[216:217]
	v_pk_mul_f32 v[84:85], v[84:85], v[218:219]
	v_pk_mul_f32 v[86:87], v[86:87], v[220:221]
	v_pk_mul_f32 v[80:81], v[80:81], v[222:223]
	v_pk_mul_f32 v[82:83], v[82:83], v[224:225]
	global_store_dwordx4 v129, v[92:95], s[76:77]
	global_store_dwordx4 v129, v[88:91], s[76:77] offset:16
	global_store_dwordx4 v129, v[84:87], s[76:77] offset:128
	global_store_dwordx4 v129, v[80:83], s[76:77] offset:144
	s_add_u32 s76, s76, 0x10000
	s_addc_u32 s77, s77, 0
	v_pk_mul_f32 v[76:77], v[76:77], v[200:201] op_sel_hi:[1,0]
	v_pk_mul_f32 v[78:79], v[78:79], v[200:201] op_sel_hi:[1,0]
	v_pk_mul_f32 v[72:73], v[72:73], v[200:201] op_sel_hi:[1,0]
	v_pk_mul_f32 v[74:75], v[74:75], v[200:201] op_sel_hi:[1,0]
	v_pk_mul_f32 v[68:69], v[68:69], v[200:201] op_sel_hi:[1,0]
	v_pk_mul_f32 v[70:71], v[70:71], v[200:201] op_sel_hi:[1,0]
	v_pk_mul_f32 v[64:65], v[64:65], v[200:201] op_sel_hi:[1,0]
	v_pk_mul_f32 v[66:67], v[66:67], v[200:201] op_sel_hi:[1,0]
	v_pk_mul_f32 v[76:77], v[76:77], v[210:211]
	v_pk_mul_f32 v[78:79], v[78:79], v[212:213]
	v_pk_mul_f32 v[72:73], v[72:73], v[214:215]
	v_pk_mul_f32 v[74:75], v[74:75], v[216:217]
	v_pk_mul_f32 v[68:69], v[68:69], v[218:219]
	v_pk_mul_f32 v[70:71], v[70:71], v[220:221]
	v_pk_mul_f32 v[64:65], v[64:65], v[222:223]
	v_pk_mul_f32 v[66:67], v[66:67], v[224:225]
	global_store_dwordx4 v129, v[76:79], s[76:77]
	global_store_dwordx4 v129, v[72:75], s[76:77] offset:16
	global_store_dwordx4 v129, v[68:71], s[76:77] offset:128
	global_store_dwordx4 v129, v[64:67], s[76:77] offset:144
	s_add_u32 s76, s76, 0x50000
	s_addc_u32 s77, s77, 0
	v_pk_mul_f32 v[60:61], v[60:61], v[202:203] op_sel_hi:[1,0]
	v_pk_mul_f32 v[62:63], v[62:63], v[202:203] op_sel_hi:[1,0]
	v_pk_mul_f32 v[56:57], v[56:57], v[202:203] op_sel_hi:[1,0]
	v_pk_mul_f32 v[58:59], v[58:59], v[202:203] op_sel_hi:[1,0]
	v_pk_mul_f32 v[52:53], v[52:53], v[202:203] op_sel_hi:[1,0]
	v_pk_mul_f32 v[54:55], v[54:55], v[202:203] op_sel_hi:[1,0]
	v_pk_mul_f32 v[48:49], v[48:49], v[202:203] op_sel_hi:[1,0]
	v_pk_mul_f32 v[50:51], v[50:51], v[202:203] op_sel_hi:[1,0]
	v_pk_mul_f32 v[60:61], v[60:61], v[210:211]
	v_pk_mul_f32 v[62:63], v[62:63], v[212:213]
	v_pk_mul_f32 v[56:57], v[56:57], v[214:215]
	v_pk_mul_f32 v[58:59], v[58:59], v[216:217]
	v_pk_mul_f32 v[52:53], v[52:53], v[218:219]
	v_pk_mul_f32 v[54:55], v[54:55], v[220:221]
	v_pk_mul_f32 v[48:49], v[48:49], v[222:223]
	v_pk_mul_f32 v[50:51], v[50:51], v[224:225]
	global_store_dwordx4 v129, v[60:63], s[76:77]
	global_store_dwordx4 v129, v[56:59], s[76:77] offset:16
	global_store_dwordx4 v129, v[52:55], s[76:77] offset:128
	global_store_dwordx4 v129, v[48:51], s[76:77] offset:144
	s_add_u32 s76, s76, 0x10000
	s_addc_u32 s77, s77, 0
	v_pk_mul_f32 v[44:45], v[44:45], v[204:205] op_sel_hi:[1,0]
	v_pk_mul_f32 v[46:47], v[46:47], v[204:205] op_sel_hi:[1,0]
	v_pk_mul_f32 v[40:41], v[40:41], v[204:205] op_sel_hi:[1,0]
	v_pk_mul_f32 v[42:43], v[42:43], v[204:205] op_sel_hi:[1,0]
	v_pk_mul_f32 v[36:37], v[36:37], v[204:205] op_sel_hi:[1,0]
	v_pk_mul_f32 v[38:39], v[38:39], v[204:205] op_sel_hi:[1,0]
	v_pk_mul_f32 v[32:33], v[32:33], v[204:205] op_sel_hi:[1,0]
	v_pk_mul_f32 v[34:35], v[34:35], v[204:205] op_sel_hi:[1,0]
	v_pk_mul_f32 v[44:45], v[44:45], v[210:211]
	v_pk_mul_f32 v[46:47], v[46:47], v[212:213]
	v_pk_mul_f32 v[40:41], v[40:41], v[214:215]
	v_pk_mul_f32 v[42:43], v[42:43], v[216:217]
	v_pk_mul_f32 v[36:37], v[36:37], v[218:219]
	v_pk_mul_f32 v[38:39], v[38:39], v[220:221]
	v_pk_mul_f32 v[32:33], v[32:33], v[222:223]
	v_pk_mul_f32 v[34:35], v[34:35], v[224:225]
	global_store_dwordx4 v129, v[44:47], s[76:77]
	global_store_dwordx4 v129, v[40:43], s[76:77] offset:16
	global_store_dwordx4 v129, v[36:39], s[76:77] offset:128
	global_store_dwordx4 v129, v[32:35], s[76:77] offset:144
	s_add_u32 s76, s76, 0x10000
	s_addc_u32 s77, s77, 0
	v_pk_mul_f32 v[28:29], v[28:29], v[206:207] op_sel_hi:[1,0]
	v_pk_mul_f32 v[30:31], v[30:31], v[206:207] op_sel_hi:[1,0]
	v_pk_mul_f32 v[24:25], v[24:25], v[206:207] op_sel_hi:[1,0]
	v_pk_mul_f32 v[26:27], v[26:27], v[206:207] op_sel_hi:[1,0]
	v_pk_mul_f32 v[20:21], v[20:21], v[206:207] op_sel_hi:[1,0]
	v_pk_mul_f32 v[22:23], v[22:23], v[206:207] op_sel_hi:[1,0]
	v_pk_mul_f32 v[16:17], v[16:17], v[206:207] op_sel_hi:[1,0]
	v_pk_mul_f32 v[18:19], v[18:19], v[206:207] op_sel_hi:[1,0]
	v_pk_mul_f32 v[28:29], v[28:29], v[210:211]
	v_pk_mul_f32 v[30:31], v[30:31], v[212:213]
	v_pk_mul_f32 v[24:25], v[24:25], v[214:215]
	v_pk_mul_f32 v[26:27], v[26:27], v[216:217]
	v_pk_mul_f32 v[20:21], v[20:21], v[218:219]
	v_pk_mul_f32 v[22:23], v[22:23], v[220:221]
	v_pk_mul_f32 v[16:17], v[16:17], v[222:223]
	v_pk_mul_f32 v[18:19], v[18:19], v[224:225]
	global_store_dwordx4 v129, v[28:31], s[76:77]
	global_store_dwordx4 v129, v[24:27], s[76:77] offset:16
	global_store_dwordx4 v129, v[20:23], s[76:77] offset:128
	global_store_dwordx4 v129, v[16:19], s[76:77] offset:144
	s_add_u32 s76, s76, 0x10000
	s_addc_u32 s77, s77, 0
	v_pk_mul_f32 v[12:13], v[12:13], v[208:209] op_sel_hi:[1,0]
	v_pk_mul_f32 v[14:15], v[14:15], v[208:209] op_sel_hi:[1,0]
	v_pk_mul_f32 v[8:9], v[8:9], v[208:209] op_sel_hi:[1,0]
	v_pk_mul_f32 v[10:11], v[10:11], v[208:209] op_sel_hi:[1,0]
	v_pk_mul_f32 v[4:5], v[4:5], v[208:209] op_sel_hi:[1,0]
	v_pk_mul_f32 v[6:7], v[6:7], v[208:209] op_sel_hi:[1,0]
	v_pk_mul_f32 v[0:1], v[0:1], v[208:209] op_sel_hi:[1,0]
	v_pk_mul_f32 v[2:3], v[2:3], v[208:209] op_sel_hi:[1,0]
	v_pk_mul_f32 v[12:13], v[12:13], v[210:211]
	v_pk_mul_f32 v[14:15], v[14:15], v[212:213]
	v_pk_mul_f32 v[8:9], v[8:9], v[214:215]
	v_pk_mul_f32 v[10:11], v[10:11], v[216:217]
	v_pk_mul_f32 v[4:5], v[4:5], v[218:219]
	v_pk_mul_f32 v[6:7], v[6:7], v[220:221]
	v_pk_mul_f32 v[0:1], v[0:1], v[222:223]
	v_pk_mul_f32 v[2:3], v[2:3], v[224:225]
	global_store_dwordx4 v129, v[12:15], s[76:77]
	global_store_dwordx4 v129, v[8:11], s[76:77] offset:16
	global_store_dwordx4 v129, v[4:7], s[76:77] offset:128
	global_store_dwordx4 v129, v[0:3], s[76:77] offset:144
	s_cmpk_gt_u32 s17, 0xff
	s_cbranch_scc0 .Lf11_w0_b
	s_barrier
